# levers 1+2: attention unit prologues, compiler vmcnt(0) drains between/behind the first tiles LDS-DMA issue removed (Q loads covered by the counted vmcnt before the barrier), on top of v7
# baseline (speedup 1.0000x reference)
; #define FA_WAIT_NI() do { if constexpr (NI == 5) asm volatile("s_waitcnt vmcnt(5)" ::: "memory"); else asm volatile("s_waitcnt vmcnt(4)" ::: "memory"); } while (0)
; template <int DQK, bool HAS_LSE>
; __device__ __forceinline__ void unit(LAS unsigned char* lds, const Desc& d) {
;     ...
;     f32x16 o[4];
; #pragma unroll
;     for (int db = 0; db < 4; ++db)
; #pragma unroll
;         for (int i = 0; i < 16; ++i) o[db][i] = 0.f;
;     float m = NEG, l = 0.f;
;     int kso[KINST], vso[2]; bool kpe_[KINST];
; #pragma unroll
;     for (int i = 0; i < KINST; ++i) { const int q = 64 * (KINST * w + i) + lane, row = q / KCH, pos = q % KCH;
;         const int c = (DQK == 192) ? ((pos & ~7) | ((pos & 7) ^ ((row >> 1) & 7))) : (pos ^ (row & 15));
;         kpe_[i] = (DQK == 192) && (c >= 16);
;         kso[i] = kpe_[i] ? row * (int)d.kps + 8 * (c - 16) : row * (int)d.ks + 8 * c; }
; #pragma unroll
;     for (int i = 0; i < 2; ++i) { const int q = 64 * (2 * w + i) + lane, sub = q >> 5, wi = q & 31, key = 8 * (sub >> 2) + (wi >> 2), ch = (sub & 3) * 4 + (wi & 3);
;         vso[i] = key * (int)d.vs + 8 * ch; }
;     ...
;     int koff[NKO];
; #pragma unroll
;     for (int j = 0; j < NKO; ++j) koff[j] = (DQK == 192) ? (r * KROW + 16 * ((2 * j + hi) ^ ((r >> 1) & 7))) : (r * KROW + 16 * ((2 * j + hi) ^ (r & 15)));
;     const int vfo = LDS_V + (4 * hi + ((lane & 15) >> 2)) * 64 + ((lane >> 4) & 1) * 32 + (lane & 3) * 8;
;     ...
;     constexpr int NI = KINST + 2;
;     ...
;     FA_DMA(d.t_lo, 0, 0);
;     if (d.t_lo + 1 < d.t_hi) { FA_DMA(d.t_lo + 1, 1, 1); FA_WAIT_NI(); } else { asm volatile("s_waitcnt vmcnt(0)" ::: "memory"); }
;     __builtin_amdgcn_s_barrier();
;     int slot = 0;
; #pragma unroll 1
;     for (int t = d.t_lo; t < d.t_hi; ++t) {
; __global__ void __launch_bounds__(NWAVES * 64, 2) mega_fwd(Args args) {
;     ...
;                             dsc.slope2 = __builtin_amdgcn_exp2f(-(float)(g * DH + h + 1) * (1.0f / 3.0f)) * (float)dil * LOG2E;
.LBB0_513:
	s_cmp_ge_u32 s58, s59
	s_mov_b32 s64, 0
	s_barrier
	s_cbranch_scc1 .LBB0_529
	s_lshl_b32 s4, s6, 3
	s_or_b32 s4, s47, s4
	s_add_i32 s4, s4, 1
	v_cvt_f32_i32_e32 v8, s4
	s_lshl_b32 s4, 1, s21
	v_cvt_f32_u32_e32 v9, s4
	v_and_b32_e32 v10, 15, v5
	v_mul_f32_e32 v8, 0xbeaaaaab, v8
	v_exp_f32_e32 v8, v8
	s_add_i32 s22, s56, s22
	v_lshlrev_b32_e32 v174, 2, v6
	v_bitop3_b32 v11, v6, v5, 15 bitop3:0x78
	v_mul_f32_e32 v8, v8, v9
	v_bitop3_b32 v9, v6, v10, 2 bitop3:0x36
	v_lshlrev_b32_e32 v167, 4, v9
	v_bitop3_b32 v9, v6, v10, 4 bitop3:0x36
	v_lshlrev_b32_e32 v168, 4, v9
	v_bitop3_b32 v9, v6, v10, 6 bitop3:0x36
	v_lshlrev_b32_e32 v169, 4, v9
	v_bitop3_b32 v9, v6, v10, 8 bitop3:0x36
	v_lshlrev_b32_e32 v170, 4, v9
	v_bitop3_b32 v9, v6, v10, 10 bitop3:0x36
	v_lshlrev_b32_e32 v171, 4, v9
	v_bitop3_b32 v9, v6, v10, 12 bitop3:0x36
	v_lshlrev_b32_e32 v172, 4, v9
	v_bitop3_b32 v9, v6, v10, 14 bitop3:0x36
	v_and_or_b32 v6, v0, 3, v174
	v_lshlrev_b32_e32 v5, 1, v5
	v_lshl_add_u64 v[158:159], v[2:3], 1, s[44:45]
	v_add_u32_e32 v2, s22, v4
	v_mov_b32_e32 v50, 0
	v_mul_f32_e32 v8, 0x3fb8aa3b, v8
	v_and_b32_e32 v5, 32, v5
	v_lshl_add_u32 v6, v6, 6, 0
	v_sub_u32_e32 v2, v2, v174
	v_mov_b32_e32 v51, v50
	v_lshlrev_b32_e32 v160, 8, v4
	v_lshlrev_b32_e32 v161, 4, v11
	v_lshlrev_b32_e32 v173, 4, v9
	v_or_b32_e32 v0, s22, v4
	v_add3_u32 v175, v6, v5, v7
	v_cmp_eq_f32_e64 s[40:41], 0, v8
	v_xor_b32_e32 v152, 0x80000000, v8
	v_subrev_u32_e32 v176, s62, v2
	v_mov_b32_e32 v52, v50
	v_mov_b32_e32 v53, v50
	v_mov_b32_e32 v54, v50
	v_mov_b32_e32 v55, v50
	v_mov_b32_e32 v56, v50
	v_mov_b32_e32 v57, v50
	v_mov_b32_e32 v58, v50
	v_mov_b32_e32 v59, v50
	v_mov_b32_e32 v60, v50
	v_mov_b32_e32 v61, v50
	v_mov_b32_e32 v62, v50
	v_mov_b32_e32 v63, v50
	v_mov_b32_e32 v64, v50
	v_mov_b32_e32 v65, v50
	v_mov_b64_e32 v[34:35], v[50:51]
	s_waitcnt lgkmcnt(0)
	v_mov_b64_e32 v[18:19], v[50:51]
	v_mov_b64_e32 v[2:3], v[50:51]
	s_or_b32 s65, s22, 31
	s_add_i32 s66, s22, 0xffffff80
	s_add_i32 s67, s22, 0xffffff9f
	v_mov_b32_e32 v155, v0
	v_mov_b32_e32 v156, v152
	v_mov_b32_e32 v157, v152
	v_mov_b32_e32 v67, 0xf149f2ca
	v_mov_b64_e32 v[36:37], v[52:53]
	v_mov_b64_e32 v[38:39], v[54:55]
	v_mov_b64_e32 v[40:41], v[56:57]
	v_mov_b64_e32 v[42:43], v[58:59]
	v_mov_b64_e32 v[44:45], v[60:61]
	v_mov_b64_e32 v[46:47], v[62:63]
	v_mov_b64_e32 v[48:49], v[64:65]
	v_mov_b64_e32 v[20:21], v[52:53]
	v_mov_b64_e32 v[22:23], v[54:55]
	v_mov_b64_e32 v[24:25], v[56:57]
	v_mov_b64_e32 v[26:27], v[58:59]
	v_mov_b64_e32 v[28:29], v[60:61]
	v_mov_b64_e32 v[30:31], v[62:63]
	v_mov_b64_e32 v[32:33], v[64:65]
	v_mov_b64_e32 v[4:5], v[52:53]
	v_mov_b64_e32 v[6:7], v[54:55]
	v_mov_b64_e32 v[8:9], v[56:57]
	v_mov_b64_e32 v[10:11], v[58:59]
	v_mov_b64_e32 v[12:13], v[60:61]
	v_mov_b64_e32 v[14:15], v[62:63]
	v_mov_b64_e32 v[16:17], v[64:65]
	v_mov_b32_e32 v66, v50

; template <int DQK, bool HAS_LSE>
; __device__ __forceinline__ void unit(LAS unsigned char* lds, const Desc& d) {
;     ...
;     { const bf16* qp = d.Q + (long)(32 * w + r) * d.qs + 8 * hi;
; #pragma unroll
;       for (int ks = 0; ks < NKS; ++ks) qr[ks] = *(const bf16x8*)(qp + 16 * ks); }
;     f32x16 o[4];
; #pragma unroll
;     for (int db = 0; db < 4; ++db)
; #pragma unroll
;         for (int i = 0; i < 16; ++i) o[db][i] = 0.f;
;     float m = NEG, l = 0.f;
;     int kso[KINST], vso[2]; bool kpe_[KINST];
; #pragma unroll
;     for (int i = 0; i < KINST; ++i) { const int q = 64 * (KINST * w + i) + lane, row = q / KCH, pos = q % KCH;
;         const int c = (DQK == 192) ? ((pos & ~7) | ((pos & 7) ^ ((row >> 1) & 7))) : (pos ^ (row & 15));
;         kpe_[i] = (DQK == 192) && (c >= 16);
;         kso[i] = kpe_[i] ? row * (int)d.kps + 8 * (c - 16) : row * (int)d.ks + 8 * c; }
; __global__ void __launch_bounds__(NWAVES * 64, 2) mega_fwd(Args args) {
;     ...
;                             const int v = u & 255, i = (u >> 8) & 3, bh = v >> 2, s = v & 3, b = bh / MH, h = bh % MH;
;                             const int qb = (i == 0) ? s : (i == 1) ? 7 - s : (i == 2) ? 8 + s : 15 - s;
;                             fa::Desc dsc;
;                             dsc.Q = QB + (size_t)(b * SEQ + 256 * qb) * NQ + h * QKD; dsc.qs = NQ;
;                             dsc.K = KVB + (size_t)(b * SEQ) * NKV + h * KVROW; dsc.ks = NKV;
;                             dsc.V = dsc.K + NOPE; dsc.vs = NKV; dsc.KPE = KPE + (size_t)(b * SEQ) * (MH * ROPE) + h * ROPE; dsc.kps = MH * ROPE;
;                             dsc.O = MO + (size_t)(b * SEQ + 256 * qb) * D + h * VD; dsc.os = D;
;                             dsc.LSE = nullptr; dsc.lses = 0;
;                             dsc.Q0 = 256 * qb; dsc.t_lo = 0; dsc.t_hi = 4 * qb + 4; dsc.W = 1 << 30; dsc.slope2 = 0.f;
.LBB0_1979:
	s_lshl_b32 s4, s21, 6
	s_and_b32 s15, s4, 0x3000
	s_lshl_b32 s75, s5, 8
	s_add_i32 s22, s75, s15
	s_bfe_u32 s50, s21, 0x40002
	s_mul_i32 s8, s22, 0x1800
	v_readlane_b32 s24, v253, 32
	s_mul_hi_u32 s4, s22, 0x1800
	v_readlane_b32 s25, v253, 33
	s_add_u32 s8, s24, s8
	s_addc_u32 s4, s25, s4
	s_mul_i32 s9, s50, 0x180
	s_add_u32 s8, s8, s9
	v_mov_b32_e32 v5, v204
	s_addc_u32 s9, s4, 0
	v_mov_b64_e32 v[2:3], s[8:9]
	v_readfirstlane_b32 s4, v5
	s_ashr_i32 s4, s4, 6
	v_and_b32_e32 v4, 31, v5
	s_lshl_b32 s47, s4, 5
	v_bfe_u32 v6, v5, 5, 1
	v_or_b32_e32 v0, s47, v4
	v_mad_i64_i32 v[2:3], s[8:9], v0, s11, v[2:3]
	v_lshlrev_b32_e32 v0, 4, v6
	v_lshl_add_u64 v[2:3], v[2:3], 0, v[0:1]
	global_load_dwordx4 v[98:101], v[2:3], off
	global_load_dwordx4 v[102:105], v[2:3], off offset:32
	global_load_dwordx4 v[106:109], v[2:3], off offset:64
	global_load_dwordx4 v[110:113], v[2:3], off offset:96
	global_load_dwordx4 v[114:117], v[2:3], off offset:128
	global_load_dwordx4 v[118:121], v[2:3], off offset:160
	global_load_dwordx4 v[122:125], v[2:3], off offset:192
	global_load_dwordx4 v[126:129], v[2:3], off offset:224
	global_load_dwordx4 v[130:133], v[2:3], off offset:256
	global_load_dwordx4 v[134:137], v[2:3], off offset:288
	global_load_dwordx4 v[138:141], v[2:3], off offset:320
	global_load_dwordx4 v[142:145], v[2:3], off offset:352
	v_and_b32_e32 v0, 63, v5
	s_mul_i32 s8, s4, 0xc0
	v_or_b32_e32 v3, s8, v0
	s_mov_b32 s8, 0x2aaaaaab
	v_mul_hi_i32 v2, v3, s8
	v_lshrrev_b32_e32 v7, 31, v2
	v_ashrrev_i32_e32 v2, 2, v2
	v_add_u32_e32 v2, v2, v7
	v_mul_lo_u32 v7, v2, 24
	v_sub_u32_e32 v3, v3, v7
	v_lshrrev_b32_e32 v7, 1, v2
	v_bitop3_b32 v3, v7, v3, 7 bitop3:0x6c
	v_cmp_lt_i32_e64 s[36:37], 15, v3
	v_cmp_gt_i32_e32 vcc, 16, v3
	v_lshlrev_b32_e32 v3, 3, v3
	s_and_saveexec_b64 s[8:9], vcc
	s_xor_b64 s[8:9], exec, s[8:9]
	v_lshl_add_u32 v168, v2, 12, v3
	s_andn2_saveexec_b64 s[8:9], s[8:9]
	v_lshlrev_b32_e32 v2, 10, v2
	s_movk_i32 s14, 0xff80
	v_add3_u32 v168, v2, v3, s14
	s_or_b64 exec, exec, s[8:9]
	s_mul_i32 s24, s4, 3
	s_add_i32 s14, s24, 1
	v_lshl_or_b32 v3, s14, 6, v0
	s_mov_b32 s8, 0x2aaaaaab
	v_mul_hi_i32 v2, v3, s8
	v_lshrrev_b32_e32 v7, 31, v2
	v_ashrrev_i32_e32 v2, 2, v2
	v_add_u32_e32 v2, v2, v7
	v_mul_lo_u32 v7, v2, 24
	v_sub_u32_e32 v3, v3, v7
	v_lshrrev_b32_e32 v7, 1, v2
	v_bitop3_b32 v3, v7, v3, 7 bitop3:0x6c
	v_cmp_lt_i32_e64 s[38:39], 15, v3
	v_cmp_gt_i32_e32 vcc, 16, v3
	v_lshlrev_b32_e32 v3, 3, v3
	s_and_saveexec_b64 s[8:9], vcc
	s_xor_b64 s[8:9], exec, s[8:9]
	v_lshl_add_u32 v170, v2, 12, v3
	s_andn2_saveexec_b64 s[8:9], s[8:9]
	v_lshlrev_b32_e32 v2, 10, v2
	s_movk_i32 s25, 0xff80
	v_add3_u32 v170, v2, v3, s25
	s_or_b64 exec, exec, s[8:9]
	s_lshl_b32 s8, s15, 13
	v_readlane_b32 s26, v253, 34
	v_readlane_b32 s27, v253, 35
	s_add_u32 s8, s26, s8
	s_addc_u32 s9, s27, 0
	s_lshl_b32 s25, s50, 9
	s_add_u32 s8, s8, s25
	s_addc_u32 s9, s9, 0
	s_lshl_b32 s15, s15, 11
	v_readlane_b32 s26, v253, 36
	v_readlane_b32 s27, v253, 37
	s_add_u32 s15, s26, s15
	s_addc_u32 s25, s27, 0
	s_lshl_b32 s26, s50, 7
	s_add_u32 s42, s15, s26
	s_addc_u32 s43, s25, 0
	s_add_i32 s15, s24, 2
	v_lshl_or_b32 v2, s15, 6, v0
	s_mov_b32 s24, 0x2aaaaaab
	v_mul_hi_i32 v0, v2, s24
	v_lshrrev_b32_e32 v3, 31, v0
	v_ashrrev_i32_e32 v0, 2, v0
	v_add_u32_e32 v0, v0, v3
	v_mul_lo_u32 v3, v0, 24
	v_sub_u32_e32 v2, v2, v3
	v_lshrrev_b32_e32 v3, 1, v0
	v_bitop3_b32 v2, v3, v2, 7 bitop3:0x6c
	v_cmp_lt_i32_e64 s[40:41], 15, v2
	v_cmp_gt_i32_e32 vcc, 16, v2
	v_lshlrev_b32_e32 v7, 3, v2
	s_and_saveexec_b64 s[24:25], vcc
	s_xor_b64 s[44:45], exec, s[24:25]
	v_lshl_add_u32 v172, v0, 12, v7
	s_or_saveexec_b64 s[44:45], s[44:45]
	v_mov_b64_e32 v[2:3], s[8:9]
	s_xor_b64 exec, exec, s[44:45]
	v_lshlrev_b32_e32 v0, 10, v0
	s_movk_i32 s24, 0xff80
	v_add3_u32 v172, v0, v7, s24
	v_mov_b64_e32 v[2:3], s[42:43]
	s_or_b64 exec, exec, s[44:45]
	s_lshr_b32 s24, s21, 2
	s_lshl_b32 s51, s5, 2
	s_lshl_b32 s5, s16, 11
	s_and_b32 s24, s24, 15
	s_and_b32 s5, s5, 0x1800000
	s_lshl_b32 s25, s24, 7
	s_add_i32 s51, s51, 4
	s_add_i32 s52, s47, s75
	s_or_b32 s5, s5, s25
	s_add_u32 s53, s5, 0x2d640000
	s_addc_u32 s56, 0, 0
	s_lshl_b32 s5, s16, 13
	v_lshlrev_b32_e32 v0, 10, v5
	s_and_b32 s5, s5, 0x6000000
	s_lshl_b32 s24, s24, 9
	v_and_b32_e32 v0, 0x7000, v0
	v_lshlrev_b32_e32 v7, 3, v5
	s_or_b32 s44, s5, s24
	v_lshl_or_b32 v0, s4, 15, v0
	v_and_b32_e32 v7, 24, v7
	v_and_b32_e32 v8, 32, v5
	s_add_u32 s57, s44, 0x25700000
	v_or3_b32 v8, v0, v8, v7
	v_mov_b32_e32 v0, s9
	v_mov_b32_e32 v9, s43
	v_mov_b32_e32 v11, s8
	v_mov_b32_e32 v16, s42
	v_ashrrev_i32_e32 v169, 31, v168
	s_mul_i32 s59, s4, 0xc00
	s_addc_u32 s58, 0, 0
	v_cndmask_b32_e64 v13, v0, v9, s[36:37]
	v_cndmask_b32_e64 v12, v11, v16, s[36:37]
	v_lshlrev_b64 v[14:15], 1, v[168:169]
; #define FA_WAIT_NI() do { if constexpr (NI == 5) asm volatile("s_waitcnt vmcnt(5)" ::: "memory"); else asm volatile("s_waitcnt vmcnt(4)" ::: "memory"); } while (0)
; template <int DQK, bool HAS_LSE>
; __device__ __forceinline__ void unit(LAS unsigned char* lds, const Desc& d) {
;     ...
;     int koff[NKO];
; #pragma unroll
;     for (int j = 0; j < NKO; ++j) koff[j] = (DQK == 192) ? (r * KROW + 16 * ((2 * j + hi) ^ ((r >> 1) & 7))) : (r * KROW + 16 * ((2 * j + hi) ^ (r & 15)));
;     const int vfo = LDS_V + (4 * hi + ((lane & 15) >> 2)) * 64 + ((lane >> 4) & 1) * 32 + (lane & 3) * 8;
;     ...
;     constexpr int NI = KINST + 2;
;     ...
;     FA_DMA(d.t_lo, 0, 0);
;     if (d.t_lo + 1 < d.t_hi) { FA_DMA(d.t_lo + 1, 1, 1); FA_WAIT_NI(); } else { asm volatile("s_waitcnt vmcnt(0)" ::: "memory"); }
;     __builtin_amdgcn_s_barrier();
;     int slot = 0;
	s_add_i32 s24, s59, 0
	v_lshl_add_u64 v[12:13], v[12:13], 0, v[14:15]
	s_mov_b32 m0, s24
	v_ashrrev_i32_e32 v171, 31, v170
	s_lshl_b32 s62, s14, 10
	global_load_lds_dwordx4 v[12:13], off
	v_cndmask_b32_e64 v13, v0, v9, s[38:39]
	v_cndmask_b32_e64 v12, v11, v16, s[38:39]
	v_lshlrev_b64 v[16:17], 1, v[170:171]
	s_add_i32 s14, s62, 0
	v_lshl_add_u64 v[12:13], v[12:13], 0, v[16:17]
	s_mov_b32 m0, s14
	v_ashrrev_i32_e32 v173, 31, v172
	s_lshl_b32 s63, s15, 10
	global_load_lds_dwordx4 v[12:13], off
	v_lshlrev_b64 v[12:13], 1, v[172:173]
	s_add_i32 s15, s63, 0
	v_lshl_add_u64 v[2:3], v[2:3], 0, v[12:13]
	s_mov_b32 m0, s15
	s_lshl_b32 s4, s4, 11
	v_ashrrev_i32_e32 v9, 31, v8
	global_load_lds_dwordx4 v[2:3], off
	s_add_i32 s25, s4, 0
	v_lshlrev_b64 v[2:3], 1, v[8:9]
	v_or_b32_e32 v10, 64, v8
	s_add_i32 s64, s25, 0x12000
	v_lshl_add_u64 v[8:9], s[8:9], 0, v[2:3]
	s_mov_b64 s[4:5], 0x100
	v_lshl_add_u64 v[18:19], v[8:9], 0, s[4:5]
	s_mov_b32 m0, s64
	s_mov_b64 s[4:5], 0x180
	global_load_lds_dwordx4 v[18:19], off
	s_add_i32 m0, s25, 0x12400
	v_lshl_add_u64 v[8:9], v[8:9], 0, s[4:5]
	s_add_u32 s4, s8, 0x80000
	s_addc_u32 s5, s9, 0
	s_add_u32 s26, s42, 0x20000
	s_addc_u32 s27, s43, 0
	v_mov_b32_e32 v0, s5
	v_mov_b32_e32 v18, s27
	v_mov_b32_e32 v19, s4
	v_mov_b32_e32 v20, s26
	global_load_lds_dwordx4 v[8:9], off
	v_cndmask_b32_e64 v9, v0, v18, s[36:37]
	v_cndmask_b32_e64 v8, v19, v20, s[36:37]
	v_lshl_add_u64 v[8:9], v[8:9], 0, v[14:15]
	s_add_i32 m0, s24, 0x6000
	v_ashrrev_i32_e32 v11, 31, v10
	global_load_lds_dwordx4 v[8:9], off
	v_cndmask_b32_e64 v9, v0, v18, s[38:39]
	v_cndmask_b32_e64 v8, v19, v20, s[38:39]
	v_lshl_add_u64 v[8:9], v[8:9], 0, v[16:17]
	s_add_i32 m0, s14, 0x6000
	v_lshlrev_b32_e32 v182, 2, v6
	global_load_lds_dwordx4 v[8:9], off
	s_add_i32 m0, s15, 0x6000
	v_cndmask_b32_e64 v9, v0, v18, s[40:41]
	v_cndmask_b32_e64 v8, v19, v20, s[40:41]
	s_add_u32 s4, s8, 0x80100
	v_lshl_add_u64 v[8:9], v[8:9], 0, v[12:13]
	s_addc_u32 s5, s9, 0
	global_load_lds_dwordx4 v[8:9], off
	s_add_i32 m0, s25, 0x16000
	v_lshl_add_u64 v[8:9], s[4:5], 0, v[2:3]
	global_load_lds_dwordx4 v[8:9], off
	v_lshl_add_u64 v[8:9], v[10:11], 1, s[4:5]
	s_add_i32 m0, s25, 0x16400
	v_lshrrev_b32_e32 v0, 2, v5
	global_load_lds_dwordx4 v[8:9], off
	v_lshrrev_b32_e32 v8, 1, v5
	v_bfe_u32 v9, v5, 1, 3
	v_bitop3_b32 v8, v6, v8, 7 bitop3:0x78
	v_and_or_b32 v0, v0, 3, v182
	v_lshlrev_b32_e32 v5, 1, v5
	v_lshlrev_b32_e32 v178, 4, v8
	v_bitop3_b32 v8, v6, v9, 2 bitop3:0x36
	v_and_b32_e32 v5, 32, v5
	v_lshlrev_b32_e32 v0, 6, v0
	v_lshlrev_b32_e32 v179, 4, v8
	v_bitop3_b32 v8, v6, v9, 4 bitop3:0x36
	v_add3_u32 v0, 0, v0, v5
	s_mov_b32 s4, 0x12000
	s_mov_b32 s45, s23
	v_lshlrev_b32_e32 v180, 4, v8
	v_bitop3_b32 v8, v6, v9, 6 bitop3:0x36
	v_add3_u32 v183, v0, v7, s4
	v_add_u32_e32 v0, s52, v4
	v_mov_b32_e32 v14, v1
	v_mov_b32_e32 v15, v1
	v_mul_u32_u24_e32 v175, 0x180, v4
	v_lshlrev_b32_e32 v181, 4, v8
	v_or_b32_e32 v174, s52, v4
	s_waitcnt vmcnt(5)
	v_sub_u32_e32 v184, v0, v182
	v_lshl_add_u64 v[176:177], s[44:45], 0, v[2:3]
	v_mov_b32_e32 v0, v1
	v_mov_b32_e32 v2, v1
	v_mov_b32_e32 v3, v1
	v_mov_b32_e32 v4, v1
	v_mov_b32_e32 v5, v1
	v_mov_b32_e32 v6, v1
	v_mov_b32_e32 v7, v1
	v_mov_b32_e32 v8, v1
	v_mov_b32_e32 v9, v1
	v_mov_b32_e32 v10, v1
	v_mov_b32_e32 v11, v1
	v_mov_b32_e32 v12, v1
	v_mov_b32_e32 v13, v1
	v_mov_b64_e32 v[64:65], v[14:15]
	v_mov_b64_e32 v[48:49], v[14:15]
	s_waitcnt lgkmcnt(0)
	v_mov_b64_e32 v[32:33], v[14:15]
	v_mov_b64_e32 v[62:63], v[12:13]
	v_mov_b64_e32 v[60:61], v[10:11]
	v_mov_b64_e32 v[58:59], v[8:9]
	v_mov_b64_e32 v[56:57], v[6:7]
	v_mov_b64_e32 v[54:55], v[4:5]
	v_mov_b64_e32 v[52:53], v[2:3]
	v_mov_b64_e32 v[50:51], v[0:1]
	v_mov_b64_e32 v[46:47], v[12:13]
	v_mov_b64_e32 v[44:45], v[10:11]
	v_mov_b64_e32 v[42:43], v[8:9]
	v_mov_b64_e32 v[40:41], v[6:7]
	v_mov_b64_e32 v[38:39], v[4:5]
	v_mov_b64_e32 v[36:37], v[2:3]
	v_mov_b64_e32 v[34:35], v[0:1]
	v_mov_b64_e32 v[30:31], v[12:13]
	v_mov_b64_e32 v[28:29], v[10:11]
	v_mov_b64_e32 v[26:27], v[8:9]
	v_mov_b64_e32 v[24:25], v[6:7]
	v_mov_b64_e32 v[22:23], v[4:5]
	v_mov_b64_e32 v[20:21], v[2:3]
	v_mov_b64_e32 v[18:19], v[0:1]
	v_mov_b64_e32 v[16:17], v[14:15]
	s_mov_b32 s65, 2
	s_or_b32 s66, s52, 31
	s_add_i32 s67, s52, -2.0
	s_add_i32 s74, s52, 0xc000001f
	v_mov_b32_e32 v167, v174
	s_addk_i32 s75, 0x100
	s_mov_b32 s44, 0
	v_mov_b32_e32 v188, 0xf149f2ca
	v_mov_b32_e32 v187, 0
	v_mov_b64_e32 v[14:15], v[12:13]
	v_mov_b64_e32 v[12:13], v[10:11]
	v_mov_b64_e32 v[10:11], v[8:9]
	v_mov_b64_e32 v[8:9], v[6:7]
	v_mov_b64_e32 v[6:7], v[4:5]
	v_mov_b64_e32 v[4:5], v[2:3]
	v_mov_b64_e32 v[2:3], v[0:1]
	s_mov_b32 s45, 0
	s_barrier
	s_cmp_ge_u32 s65, s51
	s_cselect_b64 s[8:9], -1, 0
	s_and_b64 vcc, exec, s[8:9]
	s_cbranch_vccnz .LBB0_1994
	s_branch .LBB0_1993
